# chain-GEMM epilogue pipelined loads; hgrn pass-A staging loads batched; hgrn-A units rebalanced 2/6 vs x-attn
# speedup vs baseline: 1.0980x; 1.0980x over previous
.LBB0_631:
	s_or_b64 exec, exec, s[0:1]
	v_readlane_b32 s4, v251, 8
	v_readlane_b32 s10, v251, 14
	v_readlane_b32 s11, v251, 15
	s_add_u32 s0, s10, 0x3000000
	v_writelane_b32 v252, s0, 17
	s_addc_u32 s0, s11, 0
	v_readlane_b32 s8, v251, 12
	v_readlane_b32 s9, v251, 13
	s_add_u32 s38, s10, 0x40000
	s_addc_u32 s39, s11, 0
	v_readlane_b32 s8, v251, 0
	v_readlane_b32 s9, v251, 1
	s_cmpk_lt_i32 s8, 0x400
	s_cselect_b64 s[18:19], -1, 0
	s_ashr_i32 s9, s8, 31
	v_writelane_b32 v252, s0, 18
	s_lshr_b32 s0, s9, 29
	s_add_i32 s0, s8, s0
	s_ashr_i32 s12, s0, 3
	s_and_b32 s0, s0, -8
	s_sub_i32 s16, s8, s0
	s_cmp_gt_i32 s16, -1
	s_cselect_b64 s[0:1], -1, 0
	v_writelane_b32 v252, s0, 19
	v_readlane_b32 s14, v251, 4
	s_lshl_b32 s2, s16, 7
	v_writelane_b32 v252, s1, 20
	s_ashr_i32 s0, s14, 31
	s_add_u32 s46, s10, 0x17600000
	s_addc_u32 s47, s11, 0
	v_writelane_b32 v252, s0, 21
	s_add_u32 s0, s10, 0x14600000
	s_addc_u32 s1, s11, 0
	s_add_u32 s24, s10, 0x13600000
	v_writelane_b32 v252, s0, 22
	s_addc_u32 s25, s11, 0
	v_readlane_b32 s5, v251, 9
	v_writelane_b32 v252, s1, 23
	s_add_u32 s0, s10, 0x15600000
	s_addc_u32 s1, s11, 0
	v_readlane_b32 s6, v251, 10
	v_readlane_b32 s7, v251, 11
	v_readlane_b32 s15, v251, 5
	v_writelane_b32 v251, s0, 18
	s_mov_b32 s23, 0
	v_mov_b32_e32 v149, 0
	v_writelane_b32 v251, s1, 19
	s_add_u32 s0, s10, 0x12600000
	s_addc_u32 s1, s11, 0
	v_writelane_b32 v251, s0, 43
	v_mov_b32_e32 v193, 0x358637bd
	v_mov_b32_e32 v194, 1
	v_writelane_b32 v251, s1, 44
	s_add_u32 s0, s10, 0x11600000
	s_addc_u32 s1, s11, 0
	s_add_u32 s36, s10, 0x18600000
	s_addc_u32 s37, s11, 0
	s_add_u32 s17, s10, 0x7200000
	v_writelane_b32 v252, s0, 24
	s_addc_u32 s20, s11, 0
	v_mbcnt_hi_u32_b32 v191, -1, v166
	v_writelane_b32 v252, s1, 25
	s_add_u32 s0, s10, 0x148000
	s_addc_u32 s1, s11, 0
	v_writelane_b32 v252, s0, 26
	s_cmpk_lt_i32 s8, 0x300
	v_mov_b64_e32 v[150:151], 0x400
	v_writelane_b32 v252, s1, 27
	s_cselect_b64 s[0:1], -1, 0
	v_writelane_b32 v252, s0, 28
	v_mov_b64_e32 v[152:153], 0x3ff
	v_mov_b32_e32 v195, 0x41f00000
	v_writelane_b32 v252, s1, 29
	s_add_u32 s0, s10, 0x100200
	s_addc_u32 s1, s11, 0
	v_writelane_b32 v252, s0, 30
	v_mov_b32_e32 v196, 0x41b17218
	v_mov_b32_e32 v197, 0xfcf
	v_writelane_b32 v252, s1, 31
	s_add_u32 s0, s10, 0x100400
	s_addc_u32 s1, s11, 0
	v_writelane_b32 v252, s0, 32
	v_mov_b64_e32 v[154:155], 0x300
	v_mov_b64_e32 v[156:157], 0x2ff
	v_writelane_b32 v252, s1, 33
	s_add_u32 s0, s10, 0x100500
	s_addc_u32 s1, s11, 0
	v_writelane_b32 v252, s0, 34
	v_mov_b32_e32 v198, 0xff800000
	v_mov_b32_e32 v199, 0x42fe0000
	v_writelane_b32 v252, s1, 35
	s_add_u32 s0, s10, 0x100600
	s_addc_u32 s1, s11, 0
	v_writelane_b32 v252, s0, 36
	v_mov_b64_e32 v[158:159], 0x100
	v_mov_b64_e32 v[160:161], 0xff
	v_writelane_b32 v252, s1, 37
	s_add_u32 s0, s10, 0x100700
	s_addc_u32 s1, s11, 0
	v_writelane_b32 v252, s0, 38
	s_mov_b32 s77, 0x800000
	s_mov_b32 s81, 0x41000000
	v_writelane_b32 v252, s1, 39
	s_add_u32 s0, s10, 0x100800
	s_addc_u32 s1, s11, 0
	v_writelane_b32 v252, s0, 40
	s_movk_i32 s82, 0x5800
	s_mov_b64 s[84:85], 0x80
	v_writelane_b32 v252, s1, 41
	s_add_u32 s0, s10, 0x100900
	s_addc_u32 s1, s11, 0
	v_writelane_b32 v252, s0, 42
	s_mov_b64 s[86:87], 0xb000
	s_nop 0
	v_writelane_b32 v252, s1, 43
	s_add_u32 s0, s10, 0x100a00
	s_addc_u32 s1, s11, 0
	v_writelane_b32 v252, s0, 44
	s_barrier
	s_nop 0
	v_writelane_b32 v252, s1, 45
	s_add_u32 s0, s10, 0x100b00
	s_addc_u32 s1, s11, 0
	v_writelane_b32 v252, s0, 46
	s_nop 1
	v_writelane_b32 v252, s1, 47
	s_add_u32 s0, s10, 0x100c00
	s_addc_u32 s1, s11, 0
	v_writelane_b32 v252, s0, 48
	s_nop 1
	v_writelane_b32 v252, s1, 49
	s_add_u32 s0, s10, 0x100d00
	s_addc_u32 s1, s11, 0
	v_writelane_b32 v252, s0, 50
	s_nop 1
	v_writelane_b32 v252, s1, 51
	s_add_u32 s0, s10, 0x100e00
	s_addc_u32 s1, s11, 0
	v_writelane_b32 v252, s0, 52
	s_nop 1
	v_writelane_b32 v252, s1, 53
	s_add_u32 s0, s10, 0x100f00
	s_addc_u32 s1, s11, 0
	v_writelane_b32 v252, s0, 54
	s_nop 1
	v_writelane_b32 v252, s1, 55
	s_add_u32 s0, s10, 0x101000
	s_addc_u32 s1, s11, 0
	v_writelane_b32 v252, s0, 56
	s_nop 1
	v_writelane_b32 v252, s1, 57
	s_add_u32 s0, s10, 0x101100
	s_addc_u32 s1, s11, 0
	v_writelane_b32 v252, s0, 58
	s_nop 1
	v_writelane_b32 v252, s1, 59
	s_add_u32 s0, s10, 0x101200
	s_addc_u32 s1, s11, 0
	v_writelane_b32 v252, s0, 60
	s_nop 1
	v_writelane_b32 v252, s1, 61
	s_add_u32 s0, s10, 0x101300
	s_addc_u32 s1, s11, 0
	v_writelane_b32 v252, s0, 62
	s_cmp_eq_u32 s13, 15
	s_nop 0
	v_writelane_b32 v252, s1, 63
	s_cselect_b64 s[0:1], -1, 0
	v_writelane_b32 v253, s0, 0
	s_cmp_eq_u32 s13, 14
	v_readlane_b32 s4, v252, 7
	v_writelane_b32 v253, s1, 1
	s_cselect_b64 s[0:1], -1, 0
	v_writelane_b32 v253, s0, 2
	s_cmp_eq_u32 s13, 13
	v_readlane_b32 s5, v252, 8
	v_writelane_b32 v253, s1, 3
	v_readlane_b32 s0, v251, 16
	v_readlane_b32 s1, v251, 17
	s_nop 1
	v_lshl_add_u64 v[0:1], v[0:1], 2, s[0:1]
	s_mov_b64 s[0:1], 0x1400
	v_lshl_add_u64 v[146:147], v[0:1], 0, s[0:1]
	s_mov_b64 s[0:1], 0x2400
	v_lshl_add_u64 v[144:145], v[0:1], 0, s[0:1]
	s_cselect_b64 s[0:1], -1, 0
	v_writelane_b32 v253, s0, 4
	s_cmp_eq_u32 s13, 12
	s_nop 0
	v_writelane_b32 v253, s1, 5
	s_cselect_b64 s[0:1], -1, 0
	v_writelane_b32 v253, s0, 6
	s_cmp_eq_u32 s13, 11
	s_nop 0
	v_writelane_b32 v253, s1, 7
	s_cselect_b64 s[0:1], -1, 0
	v_writelane_b32 v253, s0, 8
	s_cmp_eq_u32 s13, 10
	s_nop 0
	v_writelane_b32 v253, s1, 9
	s_cselect_b64 s[0:1], -1, 0
	v_writelane_b32 v253, s0, 10
	s_cmp_eq_u32 s13, 9
	s_nop 0
	v_writelane_b32 v253, s1, 11
	s_cselect_b64 s[0:1], -1, 0
	v_writelane_b32 v253, s0, 12
	s_cmp_eq_u32 s13, 8
	s_nop 0
	v_writelane_b32 v253, s1, 13
	s_cselect_b64 s[0:1], -1, 0
	v_writelane_b32 v253, s0, 14
	s_cmp_eq_u32 s13, 7
	s_nop 0
	v_writelane_b32 v253, s1, 15
	s_cselect_b64 s[0:1], -1, 0
	v_writelane_b32 v253, s0, 16
	s_cmp_eq_u32 s13, 6
	s_nop 0
	v_writelane_b32 v253, s1, 17
	s_cselect_b64 s[0:1], -1, 0
	v_writelane_b32 v253, s0, 18
	s_cmp_eq_u32 s13, 5
	s_nop 0
	v_writelane_b32 v253, s1, 19
	s_cselect_b64 s[0:1], -1, 0
	v_writelane_b32 v253, s0, 20
	s_cmp_eq_u32 s13, 4
	s_nop 0
	v_writelane_b32 v253, s1, 21
	s_cselect_b64 s[0:1], -1, 0
	v_writelane_b32 v253, s0, 22
	s_cmp_eq_u32 s13, 3
	s_nop 0
	v_writelane_b32 v253, s1, 23
	s_cselect_b64 s[0:1], -1, 0
	v_writelane_b32 v253, s0, 24
	s_cmp_eq_u32 s13, 2
	s_nop 0
	v_writelane_b32 v253, s1, 25
	s_cselect_b64 s[0:1], -1, 0
	v_writelane_b32 v253, s0, 26
	s_cmp_eq_u32 s13, 1
	s_nop 0
	v_writelane_b32 v253, s1, 27
	s_cselect_b64 s[0:1], -1, 0
	v_writelane_b32 v253, s0, 28
	s_cmp_eq_u32 s13, 0
	s_nop 0
	v_writelane_b32 v253, s1, 29
	s_cselect_b64 s[0:1], -1, 0
	v_writelane_b32 v253, s0, 30
	s_nop 1
	v_writelane_b32 v253, s1, 31
	s_add_u32 s0, s10, 0x103400
	s_addc_u32 s1, s11, 0
	s_add_u32 s78, s10, 0x103500
	s_addc_u32 s79, s11, 0
	v_writelane_b32 v253, s0, 32
	s_cmpk_lt_i32 s8, 0x100
	s_nop 0
	v_writelane_b32 v253, s1, 33
	s_cselect_b64 s[0:1], -1, 0
	v_writelane_b32 v253, s0, 34
	s_nop 1
	v_writelane_b32 v253, s1, 35
	s_add_u32 s0, s10, 0xf600000
	v_writelane_b32 v253, s0, 36
	s_addc_u32 s0, s11, 0
	v_writelane_b32 v253, s0, 37
	s_add_u32 s0, s10, 0x10600000
	v_writelane_b32 v253, s0, 38
	s_addc_u32 s0, s11, 0
	v_writelane_b32 v253, s0, 39
	s_add_u32 s0, s10, 0x1e600000
	s_addc_u32 s1, s11, 0
	v_writelane_b32 v251, s0, 16
	s_nop 1
	v_writelane_b32 v251, s1, 17
	s_lshl_b64 s[0:1], s[8:9], 17
	s_add_u32 s4, s4, s0
	s_addc_u32 s5, s5, s1
	s_add_u32 s3, s10, 0x600000
	v_writelane_b32 v253, s3, 40
	s_addc_u32 s3, s11, 0
	v_writelane_b32 v253, s3, 41
	s_add_u32 s3, s10, 0x800000
	v_writelane_b32 v253, s3, 42
	s_addc_u32 s3, s11, 0
	v_writelane_b32 v253, s3, 43
	s_add_u32 s6, s4, 0x10000
	v_writelane_b32 v253, s4, 44
	s_addc_u32 s7, s5, 0
	s_cmpk_lg_i32 s14, 0x100
	v_writelane_b32 v253, s5, 45
	v_writelane_b32 v253, s6, 46
	s_cselect_b64 s[4:5], -1, 0
	s_add_u32 s3, s10, 0x80000
	v_writelane_b32 v253, s7, 47
	v_writelane_b32 v253, s4, 48
	s_nop 1
	v_writelane_b32 v253, s5, 49
	v_writelane_b32 v253, s3, 50
	s_addc_u32 s3, s11, 0
	v_writelane_b32 v253, s3, 51
	s_add_u32 s3, s10, 0x20600000
	v_writelane_b32 v253, s3, 52
	s_addc_u32 s3, s11, 0
	v_writelane_b32 v253, s3, 53
	s_add_i32 s3, s8, 0x80
	s_cmpk_lt_i32 s8, 0x80
	s_cselect_b64 s[4:5], -1, 0
	v_writelane_b32 v253, s4, 54
	s_nop 1
	v_writelane_b32 v253, s5, 55
	s_and_b64 s[4:5], s[4:5], exec
	s_cselect_b32 s4, 2, 6
	s_cselect_b32 s3, s8, s3
	v_writelane_b32 v253, s4, 56
	v_writelane_b32 v253, s3, 57
	s_lshl_b32 s3, s3, 6
	s_and_b32 s22, s3, 0xfc0
	s_add_u32 s4, s10, 0x41000
	s_addc_u32 s5, s11, 0
	v_writelane_b32 v253, s4, 58
	s_lshl_b32 s3, s8, 9
	s_nop 0
	v_writelane_b32 v253, s5, 59
	v_writelane_b32 v253, s3, 60
	s_lshl_b32 s3, s14, 9
	s_add_u32 s4, s10, 0x110000
	v_writelane_b32 v253, s3, 61
	s_addc_u32 s5, s11, 0
	v_writelane_b32 v253, s4, 62
	s_nop 1
	v_writelane_b32 v253, s5, 63
	s_add_u32 s4, s10, 0x13c000
	s_addc_u32 s5, s11, 0
	s_lshl_b32 s3, s16, 5
	v_writelane_b32 v254, s4, 0
	s_cmp_lt_i32 s16, 0
	s_nop 0
	v_writelane_b32 v254, s5, 1
	s_cselect_b64 s[4:5], -1, 0
	v_writelane_b32 v254, s4, 2
	s_nop 1
	v_writelane_b32 v254, s5, 3
	s_and_b64 s[4:5], s[4:5], exec
	s_mul_i32 s4, s16, 0x81
	s_cselect_b32 s2, s4, s2
	s_mul_i32 s4, s16, 33
	s_cselect_b32 s4, s4, s3
	s_movk_i32 s3, 0x61
	s_cselect_b32 s5, s3, 0x60
	s_add_i32 s2, s2, s12
	s_ashr_i32 s3, s2, 31
	s_lshr_b32 s3, s3, 24
	s_add_i32 s3, s2, s3
	s_and_b32 s6, s3, 0xff00
	s_sub_i32 s2, s2, s6
	s_sext_i32_i16 s6, s2
	s_bfe_u32 s6, s6, 0x3001c
	s_add_i32 s6, s2, s6
	s_and_b32 s7, s6, 0xfff8
	s_sub_i32 s2, s2, s7
	s_ashr_i32 s3, s3, 8
	s_lshl_b32 s3, s3, 3
	s_sext_i32_i16 s6, s6
	s_sext_i32_i16 s2, s2
	s_add_i32 s26, s3, s2
	s_ashr_i32 s2, s6, 3
	v_writelane_b32 v254, s2, 4
	s_lshr_b32 s2, s6, 3
	s_mov_b32 s6, s26
	s_ashr_i32 s27, s26, 31
	v_writelane_b32 v254, s6, 5
	s_bfe_i64 s[2:3], s[2:3], 0x100000
	s_lshl_b64 s[2:3], s[2:3], 20
	v_writelane_b32 v254, s7, 6
	s_lshl_b64 s[6:7], s[26:27], 20
	v_writelane_b32 v254, s6, 7
	s_nop 1
	v_writelane_b32 v254, s7, 8
	v_readlane_b32 s6, v251, 47
	v_readlane_b32 s7, v251, 48
	s_add_u32 s2, s6, s2
	s_addc_u32 s3, s7, s3
	v_writelane_b32 v254, s2, 9
	s_nop 1
	v_writelane_b32 v254, s3, 10
	s_mul_i32 s2, s16, s5
	s_add_i32 s2, s2, s12
	s_mul_hi_i32 s3, s2, 0x2aaaaaab
	s_lshr_b32 s5, s3, 31
	s_ashr_i32 s3, s3, 5
	s_add_i32 s3, s3, s5
	s_mul_i32 s5, s3, 0xc0
	s_sub_i32 s2, s2, s5
	s_bfe_u32 s5, s2, 0x3001c
	s_add_i32 s5, s2, s5
	s_and_b32 s6, s5, 0xfff8
	s_sub_i32 s2, s2, s6
	s_lshl_b32 s3, s3, 3
	s_sext_i32_i16 s5, s5
	s_sext_i32_i16 s2, s2
	v_writelane_b32 v254, s16, 11
	s_add_i32 s26, s3, s2
	s_ashr_i32 s2, s5, 3
	v_writelane_b32 v254, s2, 12
	s_lshr_b32 s2, s5, 3
	s_mov_b32 s6, s26
	s_ashr_i32 s27, s26, 31
	s_bfe_i64 s[2:3], s[2:3], 0x100000
	v_writelane_b32 v254, s6, 13
	s_lshl_b64 s[2:3], s[2:3], 19
	s_nop 0
	v_writelane_b32 v254, s7, 14
	s_lshl_b64 s[6:7], s[26:27], 19
	v_writelane_b32 v254, s6, 15
	s_add_u32 s2, s17, s2
	s_addc_u32 s3, s20, s3
	v_writelane_b32 v254, s7, 16
	v_writelane_b32 v254, s17, 17
	s_add_u32 s6, s2, 0x40000
	v_writelane_b32 v254, s20, 18
	s_addc_u32 s7, s3, 0
	v_writelane_b32 v254, s6, 19
	s_nop 1
	v_writelane_b32 v254, s7, 20
	s_add_u32 s6, s2, 0x40080
	v_writelane_b32 v254, s2, 21
	s_addc_u32 s7, s3, 0
	s_nop 0
	v_writelane_b32 v254, s3, 22
	s_add_i32 s2, s4, s12
	s_ashr_i32 s3, s2, 31
	s_lshr_b32 s3, s3, 26
	s_add_i32 s3, s2, s3
	s_and_b32 s4, s3, 0xffc0
	s_sub_i32 s2, s2, s4
	s_bfe_i32 s4, s2, 0x80000
	s_bfe_u32 s4, s4, 0x3000c
	s_add_i32 s4, s2, s4
	s_and_b32 s5, s4, 0xf8
	v_writelane_b32 v254, s6, 23
	s_sub_i32 s2, s2, s5
	s_ashr_i32 s3, s3, 6
	s_bfe_i32 s4, s4, 0x80000
	v_writelane_b32 v254, s7, 24
	s_lshl_b32 s3, s3, 3
	s_sext_i32_i16 s4, s4
	s_sext_i32_i8 s2, s2
	v_writelane_b32 v254, s12, 25
	s_add_i32 s6, s3, s2
	s_ashr_i32 s2, s4, 3
	v_writelane_b32 v254, s2, 26
	s_lshr_b32 s2, s4, 3
	s_mov_b32 s4, s6
	s_ashr_i32 s7, s6, 31
	v_writelane_b32 v254, s4, 27
	s_nop 1
	v_writelane_b32 v254, s5, 28
	s_lshl_b64 s[4:5], s[6:7], 19
	v_readlane_b32 s6, v251, 39
	v_readlane_b32 s7, v251, 40
	s_add_u32 s6, s6, s4
	s_addc_u32 s7, s7, s5
	s_bfe_i64 s[2:3], s[2:3], 0x100000
	s_lshl_b64 s[2:3], s[2:3], 19
	v_readlane_b32 s4, v252, 1
	v_readlane_b32 s5, v252, 2
	s_add_u32 s2, s4, s2
	s_addc_u32 s3, s5, s3
	s_add_u32 s4, s2, 0x40000
	s_addc_u32 s5, s3, 0
	v_writelane_b32 v254, s4, 29
	s_nop 1
	v_writelane_b32 v254, s5, 30
	s_add_u32 s4, s6, 0x40000
	v_writelane_b32 v254, s6, 31
	s_addc_u32 s5, s7, 0
	s_nop 0
	v_writelane_b32 v254, s7, 32
	v_writelane_b32 v254, s4, 33
	s_nop 1
	v_writelane_b32 v254, s5, 34
	s_add_u32 s4, s2, 0x40080
	v_writelane_b32 v254, s2, 35
	s_addc_u32 s5, s3, 0
	s_nop 0
	v_writelane_b32 v254, s3, 36
	v_writelane_b32 v254, s4, 37
	s_lshl_b32 s2, s8, 1
	s_nop 0
	v_writelane_b32 v254, s5, 38
	v_writelane_b32 v254, s2, 39
	s_lshl_b32 s2, s14, 1
	v_writelane_b32 v254, s2, 40
	s_add_u32 s2, s10, 0x17640080
	v_writelane_b32 v254, s2, 41
	s_addc_u32 s2, s11, 0
	s_add_u32 s0, s10, s0
	v_writelane_b32 v254, s2, 42
	s_addc_u32 s1, s11, s1
	v_writelane_b32 v254, s0, 43
	s_add_i32 s80, 0, 0x15800
	s_mov_b32 s2, 0
	v_writelane_b32 v254, s1, 44
	v_writelane_b32 v254, s18, 45
	s_mul_i32 s0, s15, s14
	v_readlane_b32 s1, v251, 2
	v_writelane_b32 v254, s19, 46
	s_mul_i32 s0, s0, s1
	s_mov_b32 s1, 0
	v_writelane_b32 v254, s0, 47
	v_writelane_b32 v251, s0, 2
	v_writelane_b32 v254, s22, 48
	v_cndmask_b32_e64 v192, 0, 1, s[18:19]
	v_writelane_b32 v251, s1, 3
	v_writelane_b32 v254, s23, 49
	v_writelane_b32 v251, s8, 0
	s_lshl_b32 s0, s8, 11
	v_writelane_b32 v254, s0, 50
	s_lshl_b32 s0, s14, 11
	v_writelane_b32 v254, s0, 51
	s_add_i32 s0, 0, 0x27fc0
	v_writelane_b32 v254, s0, 52
	s_add_i32 s0, 0, 0x27fc4
	v_writelane_b32 v254, s0, 53
	s_add_i32 s0, 0, 0x8400
	v_writelane_b32 v254, s0, 54
	s_add_i32 s0, 0, 0x11400
	v_writelane_b32 v254, s0, 55
	s_add_i32 s0, 0, 0x22800
	v_writelane_b32 v254, s0, 56
	s_add_i32 s0, 0, 0x24c00
	v_writelane_b32 v254, s0, 57
	v_writelane_b32 v254, s38, 58
	v_writelane_b32 v251, s9, 1
	v_writelane_b32 v251, s78, 41
	v_writelane_b32 v254, s39, 59
	v_writelane_b32 v254, s46, 60
	v_writelane_b32 v251, s79, 42
	v_writelane_b32 v251, s36, 6
	v_writelane_b32 v254, s47, 61
	v_writelane_b32 v254, s24, 62
	s_mov_b64 s[4:5], -1
	v_writelane_b32 v251, s37, 7
	s_mov_b32 s33, s80
	v_writelane_b32 v254, s25, 63
	s_branch .LBB0_634

.LBB0_1305:
	s_lshl_b32 s0, s6, 7
	s_add_i32 s0, s0, s13
	s_ashr_i32 s2, s0, 9
	s_ashr_i32 s3, s2, 31
	s_lshl_b32 s1, s0, 1
	v_mov_b32_e32 v8, v190
	s_lshl_b64 s[2:3], s[2:3], 12
	s_and_b32 s1, s1, 0x380
	s_or_b64 s[2:3], s[2:3], s[16:17]
	s_lshl_b32 s4, s1, 2
	v_readlane_b32 s8, v251, 18
	v_ashrrev_i32_e32 v10, 5, v8
	v_readlane_b32 s9, v251, 19
	s_add_u32 s4, s8, s4
	v_lshlrev_b32_e32 v0, 4, v8
	v_ashrrev_i32_e32 v11, 31, v10
	s_addc_u32 s5, s9, 0
	v_and_b32_e32 v148, 0x1f0, v0
	v_lshl_add_u64 v[0:1], s[2:3], 0, v[10:11]
	v_lshl_add_u64 v[4:5], s[4:5], 0, v[148:149]
	v_lshlrev_b64 v[0:1], 12, v[0:1]
	v_lshl_add_u64 v[0:1], v[4:5], 0, v[0:1]
	global_load_dwordx4 v[40:43], v[0:1], off
	v_add_u32_e32 v6, 0, v148
	s_movk_i32 s8, 0x210
	v_mad_u64_u32 v[10:11], s[4:5], v10, s8, v[6:7]
	v_add_u32_e32 v9, 0x200, v8
	v_and_b32_e32 v15, 63, v8
	v_lshlrev_b32_e32 v14, 1, v15
	v_add_u32_e32 v22, s80, v14
	v_and_b32_e32 v24, 0x7f, v8
	v_ashrrev_i32_e32 v23, 7, v8
	s_movk_i32 s7, 0x210
	v_cmp_lt_i32_e32 vcc, 0, v23
	v_mov_b32_e32 v64, v10
	v_ashrrev_i32_e32 v10, 5, v9
	v_ashrrev_i32_e32 v11, 31, v10
	v_lshl_add_u64 v[0:1], s[2:3], 0, v[10:11]
	v_lshlrev_b64 v[0:1], 12, v[0:1]
	v_lshl_add_u64 v[0:1], v[4:5], 0, v[0:1]
	global_load_dwordx4 v[44:47], v[0:1], off
	v_add_u32_e32 v0, 0x400, v8
	v_ashrrev_i32_e32 v10, 5, v0
	v_ashrrev_i32_e32 v11, 31, v10
	v_lshl_add_u64 v[0:1], s[2:3], 0, v[10:11]
	v_lshlrev_b64 v[0:1], 12, v[0:1]
	v_lshl_add_u64 v[0:1], v[4:5], 0, v[0:1]
	global_load_dwordx4 v[48:51], v[0:1], off
	v_add_u32_e32 v0, 0x600, v8
	v_ashrrev_i32_e32 v10, 5, v0
	v_ashrrev_i32_e32 v11, 31, v10
	v_lshl_add_u64 v[0:1], s[2:3], 0, v[10:11]
	v_lshlrev_b64 v[0:1], 12, v[0:1]
	v_lshl_add_u64 v[0:1], v[4:5], 0, v[0:1]
	global_load_dwordx4 v[52:55], v[0:1], off
	v_or_b32_e32 v0, s2, v15
	v_mov_b32_e32 v1, s3
	v_readlane_b32 s2, v251, 43
	v_lshlrev_b64 v[0:1], 11, v[0:1]
	v_readlane_b32 s3, v251, 44
	s_nop 1
	v_lshl_add_u64 v[2:3], s[2:3], 0, v[0:1]
	v_readlane_b32 s2, v251, 2
	v_readlane_b32 s3, v251, 3
	s_lshl_b32 s2, s1, 1
	v_lshl_add_u64 v[0:1], s[24:25], 0, v[0:1]
	v_lshl_add_u64 v[18:19], v[0:1], 0, s[2:3]
	v_ashrrev_i32_e32 v0, 3, v8
	v_and_b32_e32 v12, -8, v0
	v_ashrrev_i32_e32 v13, 31, v12
	v_lshl_add_u64 v[16:17], v[2:3], 0, s[2:3]
	v_lshlrev_b64 v[0:1], 1, v[12:13]
	v_lshl_add_u64 v[2:3], v[16:17], 0, v[0:1]
	v_lshl_add_u64 v[0:1], v[18:19], 0, v[0:1]
	global_load_dwordx4 v[4:7], v[2:3], off
	s_mov_b32 s1, s3
	global_load_dwordx4 v[56:59], v[0:1], off
	v_writelane_b32 v251, s0, 2
	s_nop 1
	v_writelane_b32 v251, s1, 3
	s_movk_i32 s1, 0x48
	v_mul_lo_u32 v13, v12, s1
	v_lshlrev_b32_e32 v10, 1, v13
	v_add_u32_e32 v65, v22, v10
	v_add3_u32 v66, s80, v10, v14
	v_ashrrev_i32_e32 v0, 3, v9
	v_and_b32_e32 v10, -8, v0
	v_ashrrev_i32_e32 v11, 31, v10
	v_lshlrev_b64 v[20:21], 1, v[10:11]
	v_lshl_add_u64 v[0:1], v[16:17], 0, v[20:21]
	v_lshl_add_u64 v[16:17], v[18:19], 0, v[20:21]
	global_load_dwordx4 v[0:3], v[0:1], off
	v_mul_lo_u32 v11, v10, s1
	global_load_dwordx4 v[16:19], v[16:17], off
	v_lshlrev_b32_e32 v9, 1, v11
	v_add_u32_e32 v20, v22, v9
	v_add3_u32 v9, s80, v9, v14
	s_movk_i32 s1, 0x2100
	s_waitcnt vmcnt(7)
	ds_write_b128 v64, v[40:43]
	s_waitcnt vmcnt(6)
	ds_write_b128 v64, v[44:47] offset:8448
	s_waitcnt vmcnt(5)
	ds_write_b128 v64, v[48:51] offset:16896
	s_waitcnt vmcnt(4)
	ds_write_b128 v64, v[52:55] offset:25344
	s_waitcnt vmcnt(2)
	ds_write_b16 v65, v56
	ds_write_b16_d16_hi v66, v56 offset:144
	ds_write_b16 v65, v57 offset:288
	ds_write_b16_d16_hi v66, v57 offset:432
	ds_write_b16 v65, v58 offset:576
	ds_write_b16_d16_hi v66, v58 offset:720
	ds_write_b16 v65, v59 offset:864
	ds_write_b16_d16_hi v66, v59 offset:1008
	s_waitcnt vmcnt(0)
	ds_write_b16 v20, v16
	ds_write_b16_d16_hi v9, v16 offset:144
	ds_write_b16 v20, v17 offset:288
	ds_write_b16_d16_hi v9, v17 offset:432
	ds_write_b16 v20, v18 offset:576
	ds_write_b16_d16_hi v9, v18 offset:720
	ds_write_b16 v20, v19 offset:864
	ds_write_b16_d16_hi v9, v19 offset:1008
	v_lshl_add_u32 v9, v24, 2, 0
	v_mul_lo_u32 v16, v23, s1
	v_add_u32_e32 v21, v9, v16
	s_waitcnt lgkmcnt(0)
	s_barrier
	ds_read2_b32 v[16:17], v21 offset1:132
	v_add_u32_e32 v22, 0x400, v21
	v_add_u32_e32 v25, 0x800, v21
	v_add_u32_e32 v19, 0xc00, v21
	v_add_u32_e32 v20, 0x1000, v21
	s_waitcnt lgkmcnt(0)
	v_add_f32_e32 v9, 0, v16
	v_add_f32_e32 v18, v9, v17
	ds_read2_b32 v[16:17], v22 offset0:8 offset1:140
	ds_write2_b32 v21, v9, v18 offset1:132
	s_waitcnt lgkmcnt(1)
	v_add_f32_e32 v9, v18, v16
	v_add_f32_e32 v18, v9, v17
	ds_read2_b32 v[16:17], v25 offset0:16 offset1:148
	ds_write2_b32 v22, v9, v18 offset0:8 offset1:140
	s_waitcnt lgkmcnt(1)
	v_add_f32_e32 v9, v18, v16
	v_add_f32_e32 v18, v9, v17
	ds_read2_b32 v[16:17], v19 offset0:24 offset1:156
	ds_write2_b32 v25, v9, v18 offset0:16 offset1:148
	s_waitcnt lgkmcnt(1)
	v_add_f32_e32 v9, v18, v16
	v_add_f32_e32 v18, v9, v17
	ds_read2_b32 v[16:17], v20 offset0:32 offset1:164
	ds_write2_b32 v19, v9, v18 offset0:24 offset1:156
	s_waitcnt lgkmcnt(1)
	v_add_f32_e32 v9, v18, v16
	v_add_f32_e32 v16, v9, v17
	v_add_u32_e32 v17, 0x1400, v21
	ds_read2_b32 v[26:27], v17 offset0:40 offset1:172
	ds_write2_b32 v20, v9, v16 offset0:32 offset1:164
	v_add_u32_e32 v18, 0x1800, v21
	s_waitcnt lgkmcnt(1)
	v_add_f32_e32 v9, v16, v26
	v_add_f32_e32 v16, v9, v27
	ds_read2_b32 v[26:27], v18 offset0:48 offset1:180
	ds_write2_b32 v17, v9, v16 offset0:40 offset1:172
	s_waitcnt lgkmcnt(1)
	v_add_f32_e32 v9, v16, v26
	v_add_f32_e32 v16, v9, v27
	ds_write2_b32 v18, v9, v16 offset0:48 offset1:180
	v_add_u32_e32 v9, 0x1c00, v21
	ds_read2_b32 v[26:27], v9 offset0:56 offset1:188
	s_waitcnt lgkmcnt(0)
	v_add_f32_e32 v16, v16, v26
	v_add_f32_e32 v26, v16, v27
	ds_write2_b32 v9, v16, v26 offset0:56 offset1:188
	v_lshl_add_u32 v16, v8, 2, 0
	ds_write_b32 v16, v26 offset:33792
	s_waitcnt lgkmcnt(0)
	s_barrier
	s_and_saveexec_b64 s[2:3], vcc
	s_cbranch_execz .LBB0_1309
	v_readlane_b32 s1, v254, 54
	s_mov_b64 s[4:5], 0
	s_nop 0
	v_lshl_add_u32 v26, v24, 2, s1
	v_mov_b32_e32 v24, 0

.LBB0_1629:
	s_mov_b32 s11, s12
	s_cmp_lt_i32 s12, 1
	s_cbranch_scc1 .Lc5_nofence
	s_waitcnt vmcnt(0) lgkmcnt(0)
	buffer_inv sc1
.Lc5_nofence:
	v_lshl_or_b32 v162, s14, 8, v176
	s_lshl_b32 s2, s13, 8
	v_add_u32_e32 v249, s2, v168
	v_readlane_b32 s14, v251, 16
	v_readlane_b32 s15, v251, 17
	v_readlane_b32 s20, v250, 1
	v_readlane_b32 s21, v250, 2
	s_lshl_b32 s3, s11, 12
	v_lshlrev_b32_e32 v162, 1, v162
	v_lshl_add_u32 v143, v249, 12, v162
	v_mov_b32_e32 v167, 0x3000
	v_mad_u32_u24 v142, v249, v167, v162
	v_add_u32_e32 v142, s3, v142
	v_mov_b32_e32 v166, v143
	s_cmp_eq_u32 s11, 2
	s_cselect_b32 s12, s20, s14
	s_cselect_b32 s13, s21, s15
	s_nop 3
	global_load_dwordx4 v[200:203], v142, s[36:37]
	global_load_dwordx4 v[204:207], v143, s[14:15]
	global_load_dwordx4 v[208:211], v142, s[36:37] offset:256
	global_load_dwordx4 v[212:215], v143, s[14:15] offset:256
	v_add_u32_e32 v142, 0x30000, v142
	v_add_u32_e32 v143, 0x10000, v143
	global_load_dwordx4 v[216:219], v142, s[36:37]
	global_load_dwordx4 v[220:223], v143, s[14:15]
	global_load_dwordx4 v[224:227], v142, s[36:37] offset:256
	global_load_dwordx4 v[228:231], v143, s[14:15] offset:256
	v_add_u32_e32 v142, 0x30000, v142
	v_add_u32_e32 v143, 0x10000, v143
	global_load_dwordx4 v[232:235], v142, s[36:37]
	global_load_dwordx4 v[236:239], v143, s[14:15]
	global_load_dwordx4 v[240:243], v142, s[36:37] offset:256
	global_load_dwordx4 v[244:247], v143, s[14:15] offset:256
	v_add_u32_e32 v142, 0x30000, v142
	v_add_u32_e32 v143, 0x10000, v143
	global_load_dwordx4 v[178:181], v142, s[36:37]
	global_load_dwordx4 v[182:185], v143, s[14:15]
	global_load_dwordx4 v[186:189], v142, s[36:37] offset:256
	global_load_dwordx4 v[138:141], v143, s[14:15] offset:256
	v_add_u32_e32 v142, 0xf0000, v142
	v_add_u32_e32 v143, 0x50000, v143
	s_waitcnt vmcnt(14)
	v_lshlrev_b32_e32 v167, 16, v200
	v_and_b32_e32 v248, 0xffff0000, v200
	v_mul_f32_e32 v124, v124, v167
	v_mul_f32_e32 v125, v125, v248
	v_lshlrev_b32_e32 v167, 16, v201
	v_and_b32_e32 v248, 0xffff0000, v201
	v_mul_f32_e32 v126, v126, v167
	v_mul_f32_e32 v127, v127, v248
	v_lshlrev_b32_e32 v167, 16, v202
	v_and_b32_e32 v248, 0xffff0000, v202
	v_mul_f32_e32 v120, v120, v167
	v_mul_f32_e32 v121, v121, v248
	v_lshlrev_b32_e32 v167, 16, v203
	v_and_b32_e32 v248, 0xffff0000, v203
	v_mul_f32_e32 v122, v122, v167
	v_mul_f32_e32 v123, v123, v248
	s_cmp_eq_u32 s11, 0
	s_cbranch_scc1 .Lc5_np0
	v_lshlrev_b32_e32 v167, 16, v204
	v_and_b32_e32 v248, 0xffff0000, v204
	v_add_f32_e32 v124, v124, v167
	v_add_f32_e32 v125, v125, v248
	v_lshlrev_b32_e32 v167, 16, v205
	v_and_b32_e32 v248, 0xffff0000, v205
	v_add_f32_e32 v126, v126, v167
	v_add_f32_e32 v127, v127, v248
	v_lshlrev_b32_e32 v167, 16, v206
	v_and_b32_e32 v248, 0xffff0000, v206
	v_add_f32_e32 v120, v120, v167
	v_add_f32_e32 v121, v121, v248
	v_lshlrev_b32_e32 v167, 16, v207
	v_and_b32_e32 v248, 0xffff0000, v207
	v_add_f32_e32 v122, v122, v167
	v_add_f32_e32 v123, v123, v248
.Lc5_np0:
	v_cvt_pk_bf16_f32 v124, v124, v125
	v_cvt_pk_bf16_f32 v125, v126, v127
	v_cvt_pk_bf16_f32 v126, v120, v121
	v_cvt_pk_bf16_f32 v127, v122, v123
	global_store_dwordx4 v166, v[124:127], s[12:13]
	global_load_dwordx4 v[200:203], v142, s[36:37]
	global_load_dwordx4 v[204:207], v143, s[14:15]
	s_waitcnt vmcnt(15)
	v_lshlrev_b32_e32 v167, 16, v208
	v_and_b32_e32 v248, 0xffff0000, v208
	v_mul_f32_e32 v116, v116, v167
	v_mul_f32_e32 v117, v117, v248
	v_lshlrev_b32_e32 v167, 16, v209
	v_and_b32_e32 v248, 0xffff0000, v209
	v_mul_f32_e32 v118, v118, v167
	v_mul_f32_e32 v119, v119, v248
	v_lshlrev_b32_e32 v167, 16, v210
	v_and_b32_e32 v248, 0xffff0000, v210
	v_mul_f32_e32 v112, v112, v167
	v_mul_f32_e32 v113, v113, v248
	v_lshlrev_b32_e32 v167, 16, v211
	v_and_b32_e32 v248, 0xffff0000, v211
	v_mul_f32_e32 v114, v114, v167
	v_mul_f32_e32 v115, v115, v248
	s_cmp_eq_u32 s11, 0
	s_cbranch_scc1 .Lc5_np1
	v_lshlrev_b32_e32 v167, 16, v212
	v_and_b32_e32 v248, 0xffff0000, v212
	v_add_f32_e32 v116, v116, v167
	v_add_f32_e32 v117, v117, v248
	v_lshlrev_b32_e32 v167, 16, v213
	v_and_b32_e32 v248, 0xffff0000, v213
	v_add_f32_e32 v118, v118, v167
	v_add_f32_e32 v119, v119, v248
	v_lshlrev_b32_e32 v167, 16, v214
	v_and_b32_e32 v248, 0xffff0000, v214
	v_add_f32_e32 v112, v112, v167
	v_add_f32_e32 v113, v113, v248
	v_lshlrev_b32_e32 v167, 16, v215
	v_and_b32_e32 v248, 0xffff0000, v215
	v_add_f32_e32 v114, v114, v167
	v_add_f32_e32 v115, v115, v248
.Lc5_np1:
	v_cvt_pk_bf16_f32 v116, v116, v117
	v_cvt_pk_bf16_f32 v117, v118, v119
	v_cvt_pk_bf16_f32 v118, v112, v113
	v_cvt_pk_bf16_f32 v119, v114, v115
	global_store_dwordx4 v166, v[116:119], s[12:13] offset:256
	v_add_u32_e32 v166, 0x10000, v166
	global_load_dwordx4 v[208:211], v142, s[36:37] offset:256
	global_load_dwordx4 v[212:215], v143, s[14:15] offset:256
	v_add_u32_e32 v142, 0x30000, v142
	v_add_u32_e32 v143, 0x10000, v143
	s_waitcnt vmcnt(16)
	v_lshlrev_b32_e32 v167, 16, v216
	v_and_b32_e32 v248, 0xffff0000, v216
	v_mul_f32_e32 v108, v108, v167
	v_mul_f32_e32 v109, v109, v248
	v_lshlrev_b32_e32 v167, 16, v217
	v_and_b32_e32 v248, 0xffff0000, v217
	v_mul_f32_e32 v110, v110, v167
	v_mul_f32_e32 v111, v111, v248
	v_lshlrev_b32_e32 v167, 16, v218
	v_and_b32_e32 v248, 0xffff0000, v218
	v_mul_f32_e32 v104, v104, v167
	v_mul_f32_e32 v105, v105, v248
	v_lshlrev_b32_e32 v167, 16, v219
	v_and_b32_e32 v248, 0xffff0000, v219
	v_mul_f32_e32 v106, v106, v167
	v_mul_f32_e32 v107, v107, v248
	s_cmp_eq_u32 s11, 0
	s_cbranch_scc1 .Lc5_np2
	v_lshlrev_b32_e32 v167, 16, v220
	v_and_b32_e32 v248, 0xffff0000, v220
	v_add_f32_e32 v108, v108, v167
	v_add_f32_e32 v109, v109, v248
	v_lshlrev_b32_e32 v167, 16, v221
	v_and_b32_e32 v248, 0xffff0000, v221
	v_add_f32_e32 v110, v110, v167
	v_add_f32_e32 v111, v111, v248
	v_lshlrev_b32_e32 v167, 16, v222
	v_and_b32_e32 v248, 0xffff0000, v222
	v_add_f32_e32 v104, v104, v167
	v_add_f32_e32 v105, v105, v248
	v_lshlrev_b32_e32 v167, 16, v223
	v_and_b32_e32 v248, 0xffff0000, v223
	v_add_f32_e32 v106, v106, v167
	v_add_f32_e32 v107, v107, v248
.Lc5_np2:
	v_cvt_pk_bf16_f32 v108, v108, v109
	v_cvt_pk_bf16_f32 v109, v110, v111
	v_cvt_pk_bf16_f32 v110, v104, v105
	v_cvt_pk_bf16_f32 v111, v106, v107
	global_store_dwordx4 v166, v[108:111], s[12:13]
	global_load_dwordx4 v[216:219], v142, s[36:37]
	global_load_dwordx4 v[220:223], v143, s[14:15]
	s_waitcnt vmcnt(17)
	v_lshlrev_b32_e32 v167, 16, v224
	v_and_b32_e32 v248, 0xffff0000, v224
	v_mul_f32_e32 v100, v100, v167
	v_mul_f32_e32 v101, v101, v248
	v_lshlrev_b32_e32 v167, 16, v225
	v_and_b32_e32 v248, 0xffff0000, v225
	v_mul_f32_e32 v102, v102, v167
	v_mul_f32_e32 v103, v103, v248
	v_lshlrev_b32_e32 v167, 16, v226
	v_and_b32_e32 v248, 0xffff0000, v226
	v_mul_f32_e32 v96, v96, v167
	v_mul_f32_e32 v97, v97, v248
	v_lshlrev_b32_e32 v167, 16, v227
	v_and_b32_e32 v248, 0xffff0000, v227
	v_mul_f32_e32 v98, v98, v167
	v_mul_f32_e32 v99, v99, v248
	s_cmp_eq_u32 s11, 0
	s_cbranch_scc1 .Lc5_np3
	v_lshlrev_b32_e32 v167, 16, v228
	v_and_b32_e32 v248, 0xffff0000, v228
	v_add_f32_e32 v100, v100, v167
	v_add_f32_e32 v101, v101, v248
	v_lshlrev_b32_e32 v167, 16, v229
	v_and_b32_e32 v248, 0xffff0000, v229
	v_add_f32_e32 v102, v102, v167
	v_add_f32_e32 v103, v103, v248
	v_lshlrev_b32_e32 v167, 16, v230
	v_and_b32_e32 v248, 0xffff0000, v230
	v_add_f32_e32 v96, v96, v167
	v_add_f32_e32 v97, v97, v248
	v_lshlrev_b32_e32 v167, 16, v231
	v_and_b32_e32 v248, 0xffff0000, v231
	v_add_f32_e32 v98, v98, v167
	v_add_f32_e32 v99, v99, v248
.Lc5_np3:
	v_cvt_pk_bf16_f32 v100, v100, v101
	v_cvt_pk_bf16_f32 v101, v102, v103
	v_cvt_pk_bf16_f32 v102, v96, v97
	v_cvt_pk_bf16_f32 v103, v98, v99
	global_store_dwordx4 v166, v[100:103], s[12:13] offset:256
	v_add_u32_e32 v166, 0x10000, v166
	global_load_dwordx4 v[224:227], v142, s[36:37] offset:256
	global_load_dwordx4 v[228:231], v143, s[14:15] offset:256
	v_add_u32_e32 v142, 0x30000, v142
	v_add_u32_e32 v143, 0x10000, v143
	s_waitcnt vmcnt(18)
	v_lshlrev_b32_e32 v167, 16, v232
	v_and_b32_e32 v248, 0xffff0000, v232
	v_mul_f32_e32 v92, v92, v167
	v_mul_f32_e32 v93, v93, v248
	v_lshlrev_b32_e32 v167, 16, v233
	v_and_b32_e32 v248, 0xffff0000, v233
	v_mul_f32_e32 v94, v94, v167
	v_mul_f32_e32 v95, v95, v248
	v_lshlrev_b32_e32 v167, 16, v234
	v_and_b32_e32 v248, 0xffff0000, v234
	v_mul_f32_e32 v88, v88, v167
	v_mul_f32_e32 v89, v89, v248
	v_lshlrev_b32_e32 v167, 16, v235
	v_and_b32_e32 v248, 0xffff0000, v235
	v_mul_f32_e32 v90, v90, v167
	v_mul_f32_e32 v91, v91, v248
	s_cmp_eq_u32 s11, 0
	s_cbranch_scc1 .Lc5_np4
	v_lshlrev_b32_e32 v167, 16, v236
	v_and_b32_e32 v248, 0xffff0000, v236
	v_add_f32_e32 v92, v92, v167
	v_add_f32_e32 v93, v93, v248
	v_lshlrev_b32_e32 v167, 16, v237
	v_and_b32_e32 v248, 0xffff0000, v237
	v_add_f32_e32 v94, v94, v167
	v_add_f32_e32 v95, v95, v248
	v_lshlrev_b32_e32 v167, 16, v238
	v_and_b32_e32 v248, 0xffff0000, v238
	v_add_f32_e32 v88, v88, v167
	v_add_f32_e32 v89, v89, v248
	v_lshlrev_b32_e32 v167, 16, v239
	v_and_b32_e32 v248, 0xffff0000, v239
	v_add_f32_e32 v90, v90, v167
	v_add_f32_e32 v91, v91, v248
.Lc5_np4:
	v_cvt_pk_bf16_f32 v92, v92, v93
	v_cvt_pk_bf16_f32 v93, v94, v95
	v_cvt_pk_bf16_f32 v94, v88, v89
	v_cvt_pk_bf16_f32 v95, v90, v91
	global_store_dwordx4 v166, v[92:95], s[12:13]
	global_load_dwordx4 v[232:235], v142, s[36:37]
	global_load_dwordx4 v[236:239], v143, s[14:15]
	s_waitcnt vmcnt(19)
	v_lshlrev_b32_e32 v167, 16, v240
	v_and_b32_e32 v248, 0xffff0000, v240
	v_mul_f32_e32 v84, v84, v167
	v_mul_f32_e32 v85, v85, v248
	v_lshlrev_b32_e32 v167, 16, v241
	v_and_b32_e32 v248, 0xffff0000, v241
	v_mul_f32_e32 v86, v86, v167
	v_mul_f32_e32 v87, v87, v248
	v_lshlrev_b32_e32 v167, 16, v242
	v_and_b32_e32 v248, 0xffff0000, v242
	v_mul_f32_e32 v80, v80, v167
	v_mul_f32_e32 v81, v81, v248
	v_lshlrev_b32_e32 v167, 16, v243
	v_and_b32_e32 v248, 0xffff0000, v243
	v_mul_f32_e32 v82, v82, v167
	v_mul_f32_e32 v83, v83, v248
	s_cmp_eq_u32 s11, 0
	s_cbranch_scc1 .Lc5_np5
	v_lshlrev_b32_e32 v167, 16, v244
	v_and_b32_e32 v248, 0xffff0000, v244
	v_add_f32_e32 v84, v84, v167
	v_add_f32_e32 v85, v85, v248
	v_lshlrev_b32_e32 v167, 16, v245
	v_and_b32_e32 v248, 0xffff0000, v245
	v_add_f32_e32 v86, v86, v167
	v_add_f32_e32 v87, v87, v248
	v_lshlrev_b32_e32 v167, 16, v246
	v_and_b32_e32 v248, 0xffff0000, v246
	v_add_f32_e32 v80, v80, v167
	v_add_f32_e32 v81, v81, v248
	v_lshlrev_b32_e32 v167, 16, v247
	v_and_b32_e32 v248, 0xffff0000, v247
	v_add_f32_e32 v82, v82, v167
	v_add_f32_e32 v83, v83, v248
.Lc5_np5:
	v_cvt_pk_bf16_f32 v84, v84, v85
	v_cvt_pk_bf16_f32 v85, v86, v87
	v_cvt_pk_bf16_f32 v86, v80, v81
	v_cvt_pk_bf16_f32 v87, v82, v83
	global_store_dwordx4 v166, v[84:87], s[12:13] offset:256
	v_add_u32_e32 v166, 0x10000, v166
	global_load_dwordx4 v[240:243], v142, s[36:37] offset:256
	global_load_dwordx4 v[244:247], v143, s[14:15] offset:256
	v_add_u32_e32 v142, 0x30000, v142
	v_add_u32_e32 v143, 0x10000, v143
	s_waitcnt vmcnt(20)
	v_lshlrev_b32_e32 v167, 16, v178
	v_and_b32_e32 v248, 0xffff0000, v178
	v_mul_f32_e32 v76, v76, v167
	v_mul_f32_e32 v77, v77, v248
	v_lshlrev_b32_e32 v167, 16, v179
	v_and_b32_e32 v248, 0xffff0000, v179
	v_mul_f32_e32 v78, v78, v167
	v_mul_f32_e32 v79, v79, v248
	v_lshlrev_b32_e32 v167, 16, v180
	v_and_b32_e32 v248, 0xffff0000, v180
	v_mul_f32_e32 v72, v72, v167
	v_mul_f32_e32 v73, v73, v248
	v_lshlrev_b32_e32 v167, 16, v181
	v_and_b32_e32 v248, 0xffff0000, v181
	v_mul_f32_e32 v74, v74, v167
	v_mul_f32_e32 v75, v75, v248
	s_cmp_eq_u32 s11, 0
	s_cbranch_scc1 .Lc5_np6
	v_lshlrev_b32_e32 v167, 16, v182
	v_and_b32_e32 v248, 0xffff0000, v182
	v_add_f32_e32 v76, v76, v167
	v_add_f32_e32 v77, v77, v248
	v_lshlrev_b32_e32 v167, 16, v183
	v_and_b32_e32 v248, 0xffff0000, v183
	v_add_f32_e32 v78, v78, v167
	v_add_f32_e32 v79, v79, v248
	v_lshlrev_b32_e32 v167, 16, v184
	v_and_b32_e32 v248, 0xffff0000, v184
	v_add_f32_e32 v72, v72, v167
	v_add_f32_e32 v73, v73, v248
	v_lshlrev_b32_e32 v167, 16, v185
	v_and_b32_e32 v248, 0xffff0000, v185
	v_add_f32_e32 v74, v74, v167
	v_add_f32_e32 v75, v75, v248
.Lc5_np6:
	v_cvt_pk_bf16_f32 v76, v76, v77
	v_cvt_pk_bf16_f32 v77, v78, v79
	v_cvt_pk_bf16_f32 v78, v72, v73
	v_cvt_pk_bf16_f32 v79, v74, v75
	global_store_dwordx4 v166, v[76:79], s[12:13]
	global_load_dwordx4 v[178:181], v142, s[36:37]
	global_load_dwordx4 v[182:185], v143, s[14:15]
	s_waitcnt vmcnt(21)
	v_lshlrev_b32_e32 v167, 16, v186
	v_and_b32_e32 v248, 0xffff0000, v186
	v_mul_f32_e32 v68, v68, v167
	v_mul_f32_e32 v69, v69, v248
	v_lshlrev_b32_e32 v167, 16, v187
	v_and_b32_e32 v248, 0xffff0000, v187
	v_mul_f32_e32 v70, v70, v167
	v_mul_f32_e32 v71, v71, v248
	v_lshlrev_b32_e32 v167, 16, v188
	v_and_b32_e32 v248, 0xffff0000, v188
	v_mul_f32_e32 v64, v64, v167
	v_mul_f32_e32 v65, v65, v248
	v_lshlrev_b32_e32 v167, 16, v189
	v_and_b32_e32 v248, 0xffff0000, v189
	v_mul_f32_e32 v66, v66, v167
	v_mul_f32_e32 v67, v67, v248
	s_cmp_eq_u32 s11, 0
	s_cbranch_scc1 .Lc5_np7
	v_lshlrev_b32_e32 v167, 16, v138
	v_and_b32_e32 v248, 0xffff0000, v138
	v_add_f32_e32 v68, v68, v167
	v_add_f32_e32 v69, v69, v248
	v_lshlrev_b32_e32 v167, 16, v139
	v_and_b32_e32 v248, 0xffff0000, v139
	v_add_f32_e32 v70, v70, v167
	v_add_f32_e32 v71, v71, v248
	v_lshlrev_b32_e32 v167, 16, v140
	v_and_b32_e32 v248, 0xffff0000, v140
	v_add_f32_e32 v64, v64, v167
	v_add_f32_e32 v65, v65, v248
	v_lshlrev_b32_e32 v167, 16, v141
	v_and_b32_e32 v248, 0xffff0000, v141
	v_add_f32_e32 v66, v66, v167
	v_add_f32_e32 v67, v67, v248
.Lc5_np7:
	v_cvt_pk_bf16_f32 v68, v68, v69
	v_cvt_pk_bf16_f32 v69, v70, v71
	v_cvt_pk_bf16_f32 v70, v64, v65
	v_cvt_pk_bf16_f32 v71, v66, v67
	global_store_dwordx4 v166, v[68:71], s[12:13] offset:256
	v_add_u32_e32 v166, 0x50000, v166
	global_load_dwordx4 v[186:189], v142, s[36:37] offset:256
	global_load_dwordx4 v[138:141], v143, s[14:15] offset:256
	s_waitcnt vmcnt(21)
	v_lshlrev_b32_e32 v167, 16, v200
	v_and_b32_e32 v248, 0xffff0000, v200
	v_mul_f32_e32 v60, v60, v167
	v_mul_f32_e32 v61, v61, v248
	v_lshlrev_b32_e32 v167, 16, v201
	v_and_b32_e32 v248, 0xffff0000, v201
	v_mul_f32_e32 v62, v62, v167
	v_mul_f32_e32 v63, v63, v248
	v_lshlrev_b32_e32 v167, 16, v202
	v_and_b32_e32 v248, 0xffff0000, v202
	v_mul_f32_e32 v56, v56, v167
	v_mul_f32_e32 v57, v57, v248
	v_lshlrev_b32_e32 v167, 16, v203
	v_and_b32_e32 v248, 0xffff0000, v203
	v_mul_f32_e32 v58, v58, v167
	v_mul_f32_e32 v59, v59, v248
	s_cmp_eq_u32 s11, 0
	s_cbranch_scc1 .Lc5_np8
	v_lshlrev_b32_e32 v167, 16, v204
	v_and_b32_e32 v248, 0xffff0000, v204
	v_add_f32_e32 v60, v60, v167
	v_add_f32_e32 v61, v61, v248
	v_lshlrev_b32_e32 v167, 16, v205
	v_and_b32_e32 v248, 0xffff0000, v205
	v_add_f32_e32 v62, v62, v167
	v_add_f32_e32 v63, v63, v248
	v_lshlrev_b32_e32 v167, 16, v206
	v_and_b32_e32 v248, 0xffff0000, v206
	v_add_f32_e32 v56, v56, v167
	v_add_f32_e32 v57, v57, v248
	v_lshlrev_b32_e32 v167, 16, v207
	v_and_b32_e32 v248, 0xffff0000, v207
	v_add_f32_e32 v58, v58, v167
	v_add_f32_e32 v59, v59, v248
.Lc5_np8:
	v_cvt_pk_bf16_f32 v60, v60, v61
	v_cvt_pk_bf16_f32 v61, v62, v63
	v_cvt_pk_bf16_f32 v62, v56, v57
	v_cvt_pk_bf16_f32 v63, v58, v59
	global_store_dwordx4 v166, v[60:63], s[12:13]
	s_waitcnt vmcnt(19)
	v_lshlrev_b32_e32 v167, 16, v208
	v_and_b32_e32 v248, 0xffff0000, v208
	v_mul_f32_e32 v52, v52, v167
	v_mul_f32_e32 v53, v53, v248
	v_lshlrev_b32_e32 v167, 16, v209
	v_and_b32_e32 v248, 0xffff0000, v209
	v_mul_f32_e32 v54, v54, v167
	v_mul_f32_e32 v55, v55, v248
	v_lshlrev_b32_e32 v167, 16, v210
	v_and_b32_e32 v248, 0xffff0000, v210
	v_mul_f32_e32 v48, v48, v167
	v_mul_f32_e32 v49, v49, v248
	v_lshlrev_b32_e32 v167, 16, v211
	v_and_b32_e32 v248, 0xffff0000, v211
	v_mul_f32_e32 v50, v50, v167
	v_mul_f32_e32 v51, v51, v248
	s_cmp_eq_u32 s11, 0
	s_cbranch_scc1 .Lc5_np9
	v_lshlrev_b32_e32 v167, 16, v212
	v_and_b32_e32 v248, 0xffff0000, v212
	v_add_f32_e32 v52, v52, v167
	v_add_f32_e32 v53, v53, v248
	v_lshlrev_b32_e32 v167, 16, v213
	v_and_b32_e32 v248, 0xffff0000, v213
	v_add_f32_e32 v54, v54, v167
	v_add_f32_e32 v55, v55, v248
	v_lshlrev_b32_e32 v167, 16, v214
	v_and_b32_e32 v248, 0xffff0000, v214
	v_add_f32_e32 v48, v48, v167
	v_add_f32_e32 v49, v49, v248
	v_lshlrev_b32_e32 v167, 16, v215
	v_and_b32_e32 v248, 0xffff0000, v215
	v_add_f32_e32 v50, v50, v167
	v_add_f32_e32 v51, v51, v248
.Lc5_np9:
	v_cvt_pk_bf16_f32 v52, v52, v53
	v_cvt_pk_bf16_f32 v53, v54, v55
	v_cvt_pk_bf16_f32 v54, v48, v49
	v_cvt_pk_bf16_f32 v55, v50, v51
	global_store_dwordx4 v166, v[52:55], s[12:13] offset:256
	v_add_u32_e32 v166, 0x10000, v166
	s_waitcnt vmcnt(17)
	v_lshlrev_b32_e32 v167, 16, v216
	v_and_b32_e32 v248, 0xffff0000, v216
	v_mul_f32_e32 v44, v44, v167
	v_mul_f32_e32 v45, v45, v248
	v_lshlrev_b32_e32 v167, 16, v217
	v_and_b32_e32 v248, 0xffff0000, v217
	v_mul_f32_e32 v46, v46, v167
	v_mul_f32_e32 v47, v47, v248
	v_lshlrev_b32_e32 v167, 16, v218
	v_and_b32_e32 v248, 0xffff0000, v218
	v_mul_f32_e32 v40, v40, v167
	v_mul_f32_e32 v41, v41, v248
	v_lshlrev_b32_e32 v167, 16, v219
	v_and_b32_e32 v248, 0xffff0000, v219
	v_mul_f32_e32 v42, v42, v167
	v_mul_f32_e32 v43, v43, v248
	s_cmp_eq_u32 s11, 0
	s_cbranch_scc1 .Lc5_np10
	v_lshlrev_b32_e32 v167, 16, v220
	v_and_b32_e32 v248, 0xffff0000, v220
	v_add_f32_e32 v44, v44, v167
	v_add_f32_e32 v45, v45, v248
	v_lshlrev_b32_e32 v167, 16, v221
	v_and_b32_e32 v248, 0xffff0000, v221
	v_add_f32_e32 v46, v46, v167
	v_add_f32_e32 v47, v47, v248
	v_lshlrev_b32_e32 v167, 16, v222
	v_and_b32_e32 v248, 0xffff0000, v222
	v_add_f32_e32 v40, v40, v167
	v_add_f32_e32 v41, v41, v248
	v_lshlrev_b32_e32 v167, 16, v223
	v_and_b32_e32 v248, 0xffff0000, v223
	v_add_f32_e32 v42, v42, v167
	v_add_f32_e32 v43, v43, v248
.Lc5_np10:
	v_cvt_pk_bf16_f32 v44, v44, v45
	v_cvt_pk_bf16_f32 v45, v46, v47
	v_cvt_pk_bf16_f32 v46, v40, v41
	v_cvt_pk_bf16_f32 v47, v42, v43
	global_store_dwordx4 v166, v[44:47], s[12:13]
	s_waitcnt vmcnt(15)
	v_lshlrev_b32_e32 v167, 16, v224
	v_and_b32_e32 v248, 0xffff0000, v224
	v_mul_f32_e32 v36, v36, v167
	v_mul_f32_e32 v37, v37, v248
	v_lshlrev_b32_e32 v167, 16, v225
	v_and_b32_e32 v248, 0xffff0000, v225
	v_mul_f32_e32 v38, v38, v167
	v_mul_f32_e32 v39, v39, v248
	v_lshlrev_b32_e32 v167, 16, v226
	v_and_b32_e32 v248, 0xffff0000, v226
	v_mul_f32_e32 v32, v32, v167
	v_mul_f32_e32 v33, v33, v248
	v_lshlrev_b32_e32 v167, 16, v227
	v_and_b32_e32 v248, 0xffff0000, v227
	v_mul_f32_e32 v34, v34, v167
	v_mul_f32_e32 v35, v35, v248
	s_cmp_eq_u32 s11, 0
	s_cbranch_scc1 .Lc5_np11
	v_lshlrev_b32_e32 v167, 16, v228
	v_and_b32_e32 v248, 0xffff0000, v228
	v_add_f32_e32 v36, v36, v167
	v_add_f32_e32 v37, v37, v248
	v_lshlrev_b32_e32 v167, 16, v229
	v_and_b32_e32 v248, 0xffff0000, v229
	v_add_f32_e32 v38, v38, v167
	v_add_f32_e32 v39, v39, v248
	v_lshlrev_b32_e32 v167, 16, v230
	v_and_b32_e32 v248, 0xffff0000, v230
	v_add_f32_e32 v32, v32, v167
	v_add_f32_e32 v33, v33, v248
	v_lshlrev_b32_e32 v167, 16, v231
	v_and_b32_e32 v248, 0xffff0000, v231
	v_add_f32_e32 v34, v34, v167
	v_add_f32_e32 v35, v35, v248
.Lc5_np11:
	v_cvt_pk_bf16_f32 v36, v36, v37
	v_cvt_pk_bf16_f32 v37, v38, v39
	v_cvt_pk_bf16_f32 v38, v32, v33
	v_cvt_pk_bf16_f32 v39, v34, v35
	global_store_dwordx4 v166, v[36:39], s[12:13] offset:256
	v_add_u32_e32 v166, 0x10000, v166
	s_waitcnt vmcnt(13)
	v_lshlrev_b32_e32 v167, 16, v232
	v_and_b32_e32 v248, 0xffff0000, v232
	v_mul_f32_e32 v28, v28, v167
	v_mul_f32_e32 v29, v29, v248
	v_lshlrev_b32_e32 v167, 16, v233
	v_and_b32_e32 v248, 0xffff0000, v233
	v_mul_f32_e32 v30, v30, v167
	v_mul_f32_e32 v31, v31, v248
	v_lshlrev_b32_e32 v167, 16, v234
	v_and_b32_e32 v248, 0xffff0000, v234
	v_mul_f32_e32 v24, v24, v167
	v_mul_f32_e32 v25, v25, v248
	v_lshlrev_b32_e32 v167, 16, v235
	v_and_b32_e32 v248, 0xffff0000, v235
	v_mul_f32_e32 v26, v26, v167
	v_mul_f32_e32 v27, v27, v248
	s_cmp_eq_u32 s11, 0
	s_cbranch_scc1 .Lc5_np12
	v_lshlrev_b32_e32 v167, 16, v236
	v_and_b32_e32 v248, 0xffff0000, v236
	v_add_f32_e32 v28, v28, v167
	v_add_f32_e32 v29, v29, v248
	v_lshlrev_b32_e32 v167, 16, v237
	v_and_b32_e32 v248, 0xffff0000, v237
	v_add_f32_e32 v30, v30, v167
	v_add_f32_e32 v31, v31, v248
	v_lshlrev_b32_e32 v167, 16, v238
	v_and_b32_e32 v248, 0xffff0000, v238
	v_add_f32_e32 v24, v24, v167
	v_add_f32_e32 v25, v25, v248
	v_lshlrev_b32_e32 v167, 16, v239
	v_and_b32_e32 v248, 0xffff0000, v239
	v_add_f32_e32 v26, v26, v167
	v_add_f32_e32 v27, v27, v248
.Lc5_np12:
	v_cvt_pk_bf16_f32 v28, v28, v29
	v_cvt_pk_bf16_f32 v29, v30, v31
	v_cvt_pk_bf16_f32 v30, v24, v25
	v_cvt_pk_bf16_f32 v31, v26, v27
	global_store_dwordx4 v166, v[28:31], s[12:13]
	s_waitcnt vmcnt(11)
	v_lshlrev_b32_e32 v167, 16, v240
	v_and_b32_e32 v248, 0xffff0000, v240
	v_mul_f32_e32 v20, v20, v167
	v_mul_f32_e32 v21, v21, v248
	v_lshlrev_b32_e32 v167, 16, v241
	v_and_b32_e32 v248, 0xffff0000, v241
	v_mul_f32_e32 v22, v22, v167
	v_mul_f32_e32 v23, v23, v248
	v_lshlrev_b32_e32 v167, 16, v242
	v_and_b32_e32 v248, 0xffff0000, v242
	v_mul_f32_e32 v16, v16, v167
	v_mul_f32_e32 v17, v17, v248
	v_lshlrev_b32_e32 v167, 16, v243
	v_and_b32_e32 v248, 0xffff0000, v243
	v_mul_f32_e32 v18, v18, v167
	v_mul_f32_e32 v19, v19, v248
	s_cmp_eq_u32 s11, 0
	s_cbranch_scc1 .Lc5_np13
	v_lshlrev_b32_e32 v167, 16, v244
	v_and_b32_e32 v248, 0xffff0000, v244
	v_add_f32_e32 v20, v20, v167
	v_add_f32_e32 v21, v21, v248
	v_lshlrev_b32_e32 v167, 16, v245
	v_and_b32_e32 v248, 0xffff0000, v245
	v_add_f32_e32 v22, v22, v167
	v_add_f32_e32 v23, v23, v248
	v_lshlrev_b32_e32 v167, 16, v246
	v_and_b32_e32 v248, 0xffff0000, v246
	v_add_f32_e32 v16, v16, v167
	v_add_f32_e32 v17, v17, v248
	v_lshlrev_b32_e32 v167, 16, v247
	v_and_b32_e32 v248, 0xffff0000, v247
	v_add_f32_e32 v18, v18, v167
	v_add_f32_e32 v19, v19, v248
.Lc5_np13:
	v_cvt_pk_bf16_f32 v20, v20, v21
	v_cvt_pk_bf16_f32 v21, v22, v23
	v_cvt_pk_bf16_f32 v22, v16, v17
	v_cvt_pk_bf16_f32 v23, v18, v19
	global_store_dwordx4 v166, v[20:23], s[12:13] offset:256
	v_add_u32_e32 v166, 0x10000, v166
	s_waitcnt vmcnt(9)
	v_lshlrev_b32_e32 v167, 16, v178
	v_and_b32_e32 v248, 0xffff0000, v178
	v_mul_f32_e32 v12, v12, v167
	v_mul_f32_e32 v13, v13, v248
	v_lshlrev_b32_e32 v167, 16, v179
	v_and_b32_e32 v248, 0xffff0000, v179
	v_mul_f32_e32 v14, v14, v167
	v_mul_f32_e32 v15, v15, v248
	v_lshlrev_b32_e32 v167, 16, v180
	v_and_b32_e32 v248, 0xffff0000, v180
	v_mul_f32_e32 v8, v8, v167
	v_mul_f32_e32 v9, v9, v248
	v_lshlrev_b32_e32 v167, 16, v181
	v_and_b32_e32 v248, 0xffff0000, v181
	v_mul_f32_e32 v10, v10, v167
	v_mul_f32_e32 v11, v11, v248
	s_cmp_eq_u32 s11, 0
	s_cbranch_scc1 .Lc5_np14
	v_lshlrev_b32_e32 v167, 16, v182
	v_and_b32_e32 v248, 0xffff0000, v182
	v_add_f32_e32 v12, v12, v167
	v_add_f32_e32 v13, v13, v248
	v_lshlrev_b32_e32 v167, 16, v183
	v_and_b32_e32 v248, 0xffff0000, v183
	v_add_f32_e32 v14, v14, v167
	v_add_f32_e32 v15, v15, v248
	v_lshlrev_b32_e32 v167, 16, v184
	v_and_b32_e32 v248, 0xffff0000, v184
	v_add_f32_e32 v8, v8, v167
	v_add_f32_e32 v9, v9, v248
	v_lshlrev_b32_e32 v167, 16, v185
	v_and_b32_e32 v248, 0xffff0000, v185
	v_add_f32_e32 v10, v10, v167
	v_add_f32_e32 v11, v11, v248
.Lc5_np14:
	v_cvt_pk_bf16_f32 v12, v12, v13
	v_cvt_pk_bf16_f32 v13, v14, v15
	v_cvt_pk_bf16_f32 v14, v8, v9
	v_cvt_pk_bf16_f32 v15, v10, v11
	global_store_dwordx4 v166, v[12:15], s[12:13]
	s_waitcnt vmcnt(7)
	v_lshlrev_b32_e32 v167, 16, v186
	v_and_b32_e32 v248, 0xffff0000, v186
	v_mul_f32_e32 v4, v4, v167
	v_mul_f32_e32 v5, v5, v248
	v_lshlrev_b32_e32 v167, 16, v187
	v_and_b32_e32 v248, 0xffff0000, v187
	v_mul_f32_e32 v6, v6, v167
	v_mul_f32_e32 v7, v7, v248
	v_lshlrev_b32_e32 v167, 16, v188
	v_and_b32_e32 v248, 0xffff0000, v188
	v_mul_f32_e32 v0, v0, v167
	v_mul_f32_e32 v1, v1, v248
	v_lshlrev_b32_e32 v167, 16, v189
	v_and_b32_e32 v248, 0xffff0000, v189
	v_mul_f32_e32 v2, v2, v167
	v_mul_f32_e32 v3, v3, v248
	s_cmp_eq_u32 s11, 0
	s_cbranch_scc1 .Lc5_np15
	v_lshlrev_b32_e32 v167, 16, v138
	v_and_b32_e32 v248, 0xffff0000, v138
	v_add_f32_e32 v4, v4, v167
	v_add_f32_e32 v5, v5, v248
	v_lshlrev_b32_e32 v167, 16, v139
	v_and_b32_e32 v248, 0xffff0000, v139
	v_add_f32_e32 v6, v6, v167
	v_add_f32_e32 v7, v7, v248
	v_lshlrev_b32_e32 v167, 16, v140
	v_and_b32_e32 v248, 0xffff0000, v140
	v_add_f32_e32 v0, v0, v167
	v_add_f32_e32 v1, v1, v248
	v_lshlrev_b32_e32 v167, 16, v141
	v_and_b32_e32 v248, 0xffff0000, v141
	v_add_f32_e32 v2, v2, v167
	v_add_f32_e32 v3, v3, v248
.Lc5_np15:
	v_cvt_pk_bf16_f32 v4, v4, v5
	v_cvt_pk_bf16_f32 v5, v6, v7
	v_cvt_pk_bf16_f32 v6, v0, v1
	v_cvt_pk_bf16_f32 v7, v2, v3
	global_store_dwordx4 v166, v[4:7], s[12:13] offset:256
